# FFN-up epilogue: column address calc and all 16 conv tap/bias loads issued right after the K loop, in front of the group-alignment barrier
# baseline (speedup 1.0000x reference)
.LBB0_1253:
	s_add_u32 s34, s10, 0x100
	s_addc_u32 s35, s11, 0
	s_cmp_eq_u32 vcc_hi, 28
	s_cselect_b32 s40, s5, s34
	s_cselect_b32 s41, s4, s35
	s_cselect_b32 s38, s25, s27
	s_cselect_b32 s39, s9, vcc_lo
	s_add_u32 s36, s40, 0x80
	s_addc_u32 s37, s41, 0
	s_add_i32 s75, 0, 0x10000
	s_add_i32 s46, 0, 0x14000
	v_add_u32_e32 v140, s75, v196
	v_add_u32_e32 v156, s46, v196
	ds_read_b128 v[128:131], v140
	ds_read_b128 v[132:135], v140 offset:1024
	ds_read_b128 v[136:139], v140 offset:2048
	ds_read_b128 v[140:143], v140 offset:3072
	ds_read_b128 v[144:147], v156
	ds_read_b128 v[148:151], v156 offset:1024
	ds_read_b128 v[152:155], v156 offset:2048
	ds_read_b128 v[156:159], v156 offset:3072
	s_add_u32 s10, s10, 0x80080
	s_addc_u32 s11, s11, 0
	s_add_i32 m0, s15, 0xc000
	ds_read_b128 v[160:163], v200
	ds_read_b128 v[164:167], v200 offset:1024
	ds_read_b128 v[168:171], v200 offset:2048
	ds_read_b128 v[172:175], v200 offset:3072
	ds_read_b128 v[176:179], v200 offset:4096
	ds_read_b128 v[180:183], v200 offset:5120
	ds_read_b128 v[184:187], v200 offset:6144
	ds_read_b128 v[188:191], v200 offset:7168
	s_nop 0
	global_load_lds_dwordx4 v192, s[10:11]
	s_add_i32 m0, s15, 0xe000
	s_nop 0
	global_load_lds_dwordx4 v194, s[10:11]
	s_waitcnt vmcnt(8)
	s_waitcnt lgkmcnt(0)
	s_setprio 1
	s_barrier
	v_mfma_f32_16x16x32_bf16 v[124:127], v[128:131], v[160:163], v[124:127]
	v_mfma_f32_16x16x32_bf16 v[124:127], v[132:135], v[164:167], v[124:127]
	v_mfma_f32_16x16x32_bf16 v[60:63], v[136:139], v[160:163], v[60:63]
	v_mfma_f32_16x16x32_bf16 v[60:63], v[140:143], v[164:167], v[60:63]
	v_mfma_f32_16x16x32_bf16 v[120:123], v[128:131], v[168:171], v[120:123]
	v_mfma_f32_16x16x32_bf16 v[120:123], v[132:135], v[172:175], v[120:123]
	v_mfma_f32_16x16x32_bf16 v[56:59], v[136:139], v[168:171], v[56:59]
	v_mfma_f32_16x16x32_bf16 v[56:59], v[140:143], v[172:175], v[56:59]
	v_mfma_f32_16x16x32_bf16 v[116:119], v[128:131], v[176:179], v[116:119]
	v_mfma_f32_16x16x32_bf16 v[116:119], v[132:135], v[180:183], v[116:119]
	v_mfma_f32_16x16x32_bf16 v[52:55], v[136:139], v[176:179], v[52:55]
	v_mfma_f32_16x16x32_bf16 v[52:55], v[140:143], v[180:183], v[52:55]
	v_mfma_f32_16x16x32_bf16 v[112:115], v[128:131], v[184:187], v[112:115]
	v_mfma_f32_16x16x32_bf16 v[112:115], v[132:135], v[188:191], v[112:115]
	v_mfma_f32_16x16x32_bf16 v[48:51], v[136:139], v[184:187], v[48:51]
	v_mfma_f32_16x16x32_bf16 v[48:51], v[140:143], v[188:191], v[48:51]
	v_mfma_f32_16x16x32_bf16 v[108:111], v[144:147], v[160:163], v[108:111]
	v_mfma_f32_16x16x32_bf16 v[108:111], v[148:151], v[164:167], v[108:111]
	v_mfma_f32_16x16x32_bf16 v[44:47], v[152:155], v[160:163], v[44:47]
	v_mfma_f32_16x16x32_bf16 v[44:47], v[156:159], v[164:167], v[44:47]
	v_mfma_f32_16x16x32_bf16 v[104:107], v[144:147], v[168:171], v[104:107]
	v_mfma_f32_16x16x32_bf16 v[104:107], v[148:151], v[172:175], v[104:107]
	v_mfma_f32_16x16x32_bf16 v[40:43], v[152:155], v[168:171], v[40:43]
	v_mfma_f32_16x16x32_bf16 v[40:43], v[156:159], v[172:175], v[40:43]
	v_mfma_f32_16x16x32_bf16 v[100:103], v[144:147], v[176:179], v[100:103]
	v_mfma_f32_16x16x32_bf16 v[100:103], v[148:151], v[180:183], v[100:103]
	v_mfma_f32_16x16x32_bf16 v[36:39], v[152:155], v[176:179], v[36:39]
	v_mfma_f32_16x16x32_bf16 v[36:39], v[156:159], v[180:183], v[36:39]
	v_mfma_f32_16x16x32_bf16 v[96:99], v[144:147], v[184:187], v[96:99]
	v_mfma_f32_16x16x32_bf16 v[96:99], v[148:151], v[188:191], v[96:99]
	v_mfma_f32_16x16x32_bf16 v[32:35], v[152:155], v[184:187], v[32:35]
	v_mfma_f32_16x16x32_bf16 v[32:35], v[156:159], v[188:191], v[32:35]
	s_barrier
	s_setprio 0
	s_add_i32 s47, s75, s97
	s_mov_b64 s[10:11], s[38:39]
	s_mov_b32 m0, s47
	ds_read_b128 v[160:163], v200 offset:16384
	ds_read_b128 v[164:167], v200 offset:17408
	ds_read_b128 v[168:171], v200 offset:18432
	ds_read_b128 v[172:175], v200 offset:19456
	ds_read_b128 v[176:179], v200 offset:20480
	ds_read_b128 v[180:183], v200 offset:21504
	ds_read_b128 v[184:187], v200 offset:22528
	ds_read_b128 v[188:191], v200 offset:23552
	s_nop 0
	global_load_lds_dwordx4 v193, s[10:11]
	s_add_i32 m0, s47, 0x2000
	s_nop 0
	global_load_lds_dwordx4 v195, s[10:11]
	s_add_u32 s10, s38, 0x80000
	s_addc_u32 s11, s39, 0
	s_add_i32 s46, s46, s97
	s_mov_b32 m0, s46
	s_nop 0
	global_load_lds_dwordx4 v193, s[10:11]
	s_add_i32 m0, s46, 0x2000
	s_nop 0
	global_load_lds_dwordx4 v195, s[10:11]
	s_mov_b64 s[10:11], s[40:41]
	s_mov_b32 m0, s15
	s_nop 0
	global_load_lds_dwordx4 v192, s[10:11]
	s_mov_b32 m0, s69
	s_nop 0
	global_load_lds_dwordx4 v194, s[10:11]
	s_waitcnt vmcnt(8)
	s_waitcnt lgkmcnt(0)
	s_setprio 1
	s_barrier
	v_mfma_f32_16x16x32_bf16 v[92:95], v[128:131], v[160:163], v[92:95]
	v_mfma_f32_16x16x32_bf16 v[92:95], v[132:135], v[164:167], v[92:95]
	v_mfma_f32_16x16x32_bf16 v[28:31], v[136:139], v[160:163], v[28:31]
	v_mfma_f32_16x16x32_bf16 v[28:31], v[140:143], v[164:167], v[28:31]
	v_mfma_f32_16x16x32_bf16 v[88:91], v[128:131], v[168:171], v[88:91]
	v_mfma_f32_16x16x32_bf16 v[88:91], v[132:135], v[172:175], v[88:91]
	v_mfma_f32_16x16x32_bf16 v[16:19], v[136:139], v[168:171], v[16:19]
	v_mfma_f32_16x16x32_bf16 v[16:19], v[140:143], v[172:175], v[16:19]
	v_mfma_f32_16x16x32_bf16 v[84:87], v[128:131], v[176:179], v[84:87]
	v_mfma_f32_16x16x32_bf16 v[84:87], v[132:135], v[180:183], v[84:87]
	v_mfma_f32_16x16x32_bf16 v[20:23], v[136:139], v[176:179], v[20:23]
	v_mfma_f32_16x16x32_bf16 v[20:23], v[140:143], v[180:183], v[20:23]
	v_mfma_f32_16x16x32_bf16 v[80:83], v[128:131], v[184:187], v[80:83]
	v_mfma_f32_16x16x32_bf16 v[80:83], v[132:135], v[188:191], v[80:83]
	v_mfma_f32_16x16x32_bf16 v[8:11], v[136:139], v[184:187], v[8:11]
	v_mfma_f32_16x16x32_bf16 v[8:11], v[140:143], v[188:191], v[8:11]
	v_mfma_f32_16x16x32_bf16 v[76:79], v[144:147], v[160:163], v[76:79]
	v_mfma_f32_16x16x32_bf16 v[76:79], v[148:151], v[164:167], v[76:79]
	v_mfma_f32_16x16x32_bf16 v[24:27], v[152:155], v[160:163], v[24:27]
	v_mfma_f32_16x16x32_bf16 v[24:27], v[156:159], v[164:167], v[24:27]
	v_mfma_f32_16x16x32_bf16 v[72:75], v[144:147], v[168:171], v[72:75]
	v_mfma_f32_16x16x32_bf16 v[72:75], v[148:151], v[172:175], v[72:75]
	v_mfma_f32_16x16x32_bf16 v[12:15], v[152:155], v[168:171], v[12:15]
	v_mfma_f32_16x16x32_bf16 v[12:15], v[156:159], v[172:175], v[12:15]
	v_mfma_f32_16x16x32_bf16 v[68:71], v[144:147], v[176:179], v[68:71]
	v_mfma_f32_16x16x32_bf16 v[68:71], v[148:151], v[180:183], v[68:71]
	v_mfma_f32_16x16x32_bf16 v[4:7], v[152:155], v[176:179], v[4:7]
	v_mfma_f32_16x16x32_bf16 v[4:7], v[156:159], v[180:183], v[4:7]
	v_mfma_f32_16x16x32_bf16 v[64:67], v[144:147], v[184:187], v[64:67]
	v_mfma_f32_16x16x32_bf16 v[64:67], v[148:151], v[188:191], v[64:67]
	v_mfma_f32_16x16x32_bf16 v[0:3], v[152:155], v[184:187], v[0:3]
	v_mfma_f32_16x16x32_bf16 v[0:3], v[156:159], v[188:191], v[0:3]
	s_barrier
	s_setprio 0
	s_add_i32 s46, 0, 0x18000
	s_add_i32 s47, 0, 0x1c000
	v_add_u32_e32 v140, s46, v196
	v_add_u32_e32 v156, s47, v196
	ds_read_b128 v[128:131], v140
	ds_read_b128 v[132:135], v140 offset:1024
	ds_read_b128 v[136:139], v140 offset:2048
	ds_read_b128 v[140:143], v140 offset:3072
	ds_read_b128 v[144:147], v156
	ds_read_b128 v[148:151], v156 offset:1024
	ds_read_b128 v[152:155], v156 offset:2048
	ds_read_b128 v[156:159], v156 offset:3072
	s_add_u32 s10, s40, 0x80000
	s_addc_u32 s11, s41, 0
	s_mov_b32 m0, s78
	ds_read_b128 v[160:163], v200 offset:32768
	ds_read_b128 v[164:167], v200 offset:33792
	ds_read_b128 v[168:171], v200 offset:34816
	ds_read_b128 v[172:175], v200 offset:35840
	ds_read_b128 v[176:179], v200 offset:36864
	ds_read_b128 v[180:183], v200 offset:37888
	ds_read_b128 v[184:187], v200 offset:38912
	ds_read_b128 v[188:191], v200 offset:39936
	s_nop 0
	global_load_lds_dwordx4 v192, s[10:11]
	s_mov_b32 m0, s80
	s_nop 0
	global_load_lds_dwordx4 v194, s[10:11]
	s_waitcnt vmcnt(8)
	s_waitcnt lgkmcnt(0)
	s_setprio 1
	s_barrier
	v_mfma_f32_16x16x32_bf16 v[124:127], v[128:131], v[160:163], v[124:127]
	v_mfma_f32_16x16x32_bf16 v[124:127], v[132:135], v[164:167], v[124:127]
	v_mfma_f32_16x16x32_bf16 v[60:63], v[136:139], v[160:163], v[60:63]
	v_mfma_f32_16x16x32_bf16 v[60:63], v[140:143], v[164:167], v[60:63]
	v_mfma_f32_16x16x32_bf16 v[120:123], v[128:131], v[168:171], v[120:123]
	v_mfma_f32_16x16x32_bf16 v[120:123], v[132:135], v[172:175], v[120:123]
	v_mfma_f32_16x16x32_bf16 v[56:59], v[136:139], v[168:171], v[56:59]
	v_mfma_f32_16x16x32_bf16 v[56:59], v[140:143], v[172:175], v[56:59]
	v_mfma_f32_16x16x32_bf16 v[116:119], v[128:131], v[176:179], v[116:119]
	v_mfma_f32_16x16x32_bf16 v[116:119], v[132:135], v[180:183], v[116:119]
	v_mfma_f32_16x16x32_bf16 v[52:55], v[136:139], v[176:179], v[52:55]
	v_mfma_f32_16x16x32_bf16 v[52:55], v[140:143], v[180:183], v[52:55]
	v_mfma_f32_16x16x32_bf16 v[112:115], v[128:131], v[184:187], v[112:115]
	v_mfma_f32_16x16x32_bf16 v[112:115], v[132:135], v[188:191], v[112:115]
	v_mfma_f32_16x16x32_bf16 v[48:51], v[136:139], v[184:187], v[48:51]
	v_mfma_f32_16x16x32_bf16 v[48:51], v[140:143], v[188:191], v[48:51]
	v_mfma_f32_16x16x32_bf16 v[108:111], v[144:147], v[160:163], v[108:111]
	v_mfma_f32_16x16x32_bf16 v[108:111], v[148:151], v[164:167], v[108:111]
	v_mfma_f32_16x16x32_bf16 v[44:47], v[152:155], v[160:163], v[44:47]
	v_mfma_f32_16x16x32_bf16 v[44:47], v[156:159], v[164:167], v[44:47]
	v_mfma_f32_16x16x32_bf16 v[104:107], v[144:147], v[168:171], v[104:107]
	v_mfma_f32_16x16x32_bf16 v[104:107], v[148:151], v[172:175], v[104:107]
	v_mfma_f32_16x16x32_bf16 v[40:43], v[152:155], v[168:171], v[40:43]
	v_mfma_f32_16x16x32_bf16 v[40:43], v[156:159], v[172:175], v[40:43]
	v_mfma_f32_16x16x32_bf16 v[100:103], v[144:147], v[176:179], v[100:103]
	v_mfma_f32_16x16x32_bf16 v[100:103], v[148:151], v[180:183], v[100:103]
	v_mfma_f32_16x16x32_bf16 v[36:39], v[152:155], v[176:179], v[36:39]
	v_mfma_f32_16x16x32_bf16 v[36:39], v[156:159], v[180:183], v[36:39]
	v_mfma_f32_16x16x32_bf16 v[96:99], v[144:147], v[184:187], v[96:99]
	v_mfma_f32_16x16x32_bf16 v[96:99], v[148:151], v[188:191], v[96:99]
	v_mfma_f32_16x16x32_bf16 v[32:35], v[152:155], v[184:187], v[32:35]
	v_mfma_f32_16x16x32_bf16 v[32:35], v[156:159], v[188:191], v[32:35]
	s_barrier
	s_setprio 0
	s_add_u32 s10, s38, 0x80
	s_addc_u32 s11, s39, 0
	s_add_i32 s40, s46, s97
	s_mov_b32 m0, s40
	ds_read_b128 v[160:163], v200 offset:49152
	ds_read_b128 v[164:167], v200 offset:50176
	ds_read_b128 v[168:171], v200 offset:51200
	ds_read_b128 v[172:175], v200 offset:52224
	ds_read_b128 v[176:179], v200 offset:53248
	ds_read_b128 v[180:183], v200 offset:54272
	ds_read_b128 v[184:187], v200 offset:55296
	ds_read_b128 v[188:191], v200 offset:56320
	s_nop 0
	global_load_lds_dwordx4 v193, s[10:11]
	s_add_i32 m0, s40, 0x2000
	s_nop 0
	global_load_lds_dwordx4 v195, s[10:11]
	s_add_u32 s10, s38, 0x80080
	s_addc_u32 s11, s39, 0
	s_add_i32 s38, s47, s97
	s_mov_b32 m0, s38
	s_nop 0
	global_load_lds_dwordx4 v193, s[10:11]
	s_add_i32 m0, s38, 0x2000
	s_nop 0
	global_load_lds_dwordx4 v195, s[10:11]
	s_mov_b32 m0, s85
	s_nop 0
	global_load_lds_dwordx4 v192, s[36:37]
	s_mov_b32 m0, s86
	s_nop 0
	global_load_lds_dwordx4 v194, s[36:37]
	s_waitcnt vmcnt(8)
	s_waitcnt lgkmcnt(0)
	s_setprio 1
	s_barrier
	v_mfma_f32_16x16x32_bf16 v[92:95], v[128:131], v[160:163], v[92:95]
	v_mfma_f32_16x16x32_bf16 v[92:95], v[132:135], v[164:167], v[92:95]
	v_mfma_f32_16x16x32_bf16 v[28:31], v[136:139], v[160:163], v[28:31]
	v_mfma_f32_16x16x32_bf16 v[28:31], v[140:143], v[164:167], v[28:31]
	v_mfma_f32_16x16x32_bf16 v[88:91], v[128:131], v[168:171], v[88:91]
	v_mfma_f32_16x16x32_bf16 v[88:91], v[132:135], v[172:175], v[88:91]
	v_mfma_f32_16x16x32_bf16 v[16:19], v[136:139], v[168:171], v[16:19]
	v_mfma_f32_16x16x32_bf16 v[16:19], v[140:143], v[172:175], v[16:19]
	v_mfma_f32_16x16x32_bf16 v[84:87], v[128:131], v[176:179], v[84:87]
	v_mfma_f32_16x16x32_bf16 v[84:87], v[132:135], v[180:183], v[84:87]
	v_mfma_f32_16x16x32_bf16 v[20:23], v[136:139], v[176:179], v[20:23]
	v_mfma_f32_16x16x32_bf16 v[20:23], v[140:143], v[180:183], v[20:23]
	v_mfma_f32_16x16x32_bf16 v[80:83], v[128:131], v[184:187], v[80:83]
	v_mfma_f32_16x16x32_bf16 v[80:83], v[132:135], v[188:191], v[80:83]
	v_mfma_f32_16x16x32_bf16 v[8:11], v[136:139], v[184:187], v[8:11]
	v_mfma_f32_16x16x32_bf16 v[8:11], v[140:143], v[188:191], v[8:11]
	v_mfma_f32_16x16x32_bf16 v[76:79], v[144:147], v[160:163], v[76:79]
	v_mfma_f32_16x16x32_bf16 v[76:79], v[148:151], v[164:167], v[76:79]
	v_mfma_f32_16x16x32_bf16 v[24:27], v[152:155], v[160:163], v[24:27]
	v_mfma_f32_16x16x32_bf16 v[24:27], v[156:159], v[164:167], v[24:27]
	v_mfma_f32_16x16x32_bf16 v[72:75], v[144:147], v[168:171], v[72:75]
	v_mfma_f32_16x16x32_bf16 v[72:75], v[148:151], v[172:175], v[72:75]
	v_mfma_f32_16x16x32_bf16 v[12:15], v[152:155], v[168:171], v[12:15]
	v_mfma_f32_16x16x32_bf16 v[12:15], v[156:159], v[172:175], v[12:15]
	v_mfma_f32_16x16x32_bf16 v[68:71], v[144:147], v[176:179], v[68:71]
	v_mfma_f32_16x16x32_bf16 v[68:71], v[148:151], v[180:183], v[68:71]
	v_mfma_f32_16x16x32_bf16 v[4:7], v[152:155], v[176:179], v[4:7]
	v_mfma_f32_16x16x32_bf16 v[4:7], v[156:159], v[180:183], v[4:7]
	v_mfma_f32_16x16x32_bf16 v[64:67], v[144:147], v[184:187], v[64:67]
	v_mfma_f32_16x16x32_bf16 v[64:67], v[148:151], v[188:191], v[64:67]
	v_mfma_f32_16x16x32_bf16 v[0:3], v[152:155], v[184:187], v[0:3]
	v_mfma_f32_16x16x32_bf16 v[0:3], v[156:159], v[188:191], v[0:3]
	s_barrier
	s_setprio 0
	s_add_i32 vcc_hi, vcc_hi, 2
	s_add_u32 s27, s27, 0x100
	s_addc_u32 vcc_lo, vcc_lo, 0
	s_cmp_gt_u32 vcc_hi, 29
	s_mov_b64 s[10:11], s[34:35]
	s_cbranch_scc0 .LBB0_1253
	v_mbcnt_lo_u32_b32 v205, -1, 0
	v_mbcnt_hi_u32_b32 v205, -1, v205
	v_and_b32_e32 v201, 15, v205
	v_ashrrev_i32_e32 v205, 1, v205
	v_and_b32_e32 v205, -8, v205
	v_add_u32_e32 v160, s68, v205
	v_lshl_add_u32 v176, s8, 7, v160
	v_ashrrev_i32_e32 v177, 31, v176
	v_lshlrev_b64 v[128:129], 2, v[176:177]
	v_lshl_add_u64 v[180:181], s[16:17], 0, v[128:129]
	v_add_co_u32_e32 v136, vcc, 0xb000, v180
	s_mov_b32 s4, 0x16000
	s_nop 0
	v_addc_co_u32_e32 v137, vcc, 0, v181, vcc
	v_add_co_u32_e32 v184, vcc, s4, v180
	v_lshl_add_u64 v[178:179], s[20:21], 0, v[128:129]
	s_nop 0
	v_addc_co_u32_e32 v185, vcc, 0, v181, vcc
	s_movk_i32 s4, 0x5000
	v_add_co_u32_e32 v182, vcc, s4, v178
	s_nop 0
	s_nop 0
	v_addc_co_u32_e32 v183, vcc, 0, v179, vcc
	v_add_co_u32_e32 v186, vcc, s4, v180
	s_mov_b32 s4, 0x10000
	s_nop 0
	v_addc_co_u32_e32 v187, vcc, 0, v181, vcc
	v_add_co_u32_e32 v188, vcc, s4, v180
	s_mov_b32 s4, 0x1b000
	s_nop 0
	v_addc_co_u32_e32 v189, vcc, 0, v181, vcc
	global_load_dwordx4 v[128:131], v[178:179], off
	global_load_dwordx4 v[132:135], v[180:181], off
	global_load_dwordx4 v[148:151], v[136:137], off
	global_load_dwordx4 v[216:219], v[136:137], off offset:16
	global_load_dwordx4 v[152:155], v[184:185], off
	s_nop 0
	global_load_dwordx4 v[136:139], v[182:183], off offset:2048
	global_load_dwordx4 v[140:143], v[186:187], off offset:2048
	global_load_dwordx4 v[144:147], v[188:189], off offset:2048
	v_add_co_u32_e32 v190, vcc, s4, v180
	s_nop 0
	s_nop 0
	v_addc_co_u32_e32 v191, vcc, 0, v181, vcc
	global_load_dwordx4 v[156:159], v[190:191], off offset:2048
	global_load_dwordx4 v[224:227], v[178:179], off offset:16
	global_load_dwordx4 v[228:231], v[180:181], off offset:16
	global_load_dwordx4 v[232:235], v[184:185], off offset:16
	global_load_dwordx4 v[236:239], v[188:189], off offset:2064
	global_load_dwordx4 v[240:243], v[182:183], off offset:2064
	global_load_dwordx4 v[244:247], v[186:187], off offset:2064
	global_load_dwordx4 v[248:251], v[190:191], off offset:2064
	s_and_b64 vcc, exec, s[60:61]
	s_cbranch_vccz .LBB0_1256
	s_barrier
.LBB0_1256:
	v_readlane_b32 s4, v254, 41
	s_nop 0
	v_cmp_eq_u32_e32 vcc, 0, v201
	v_lshl_add_u32 v205, v160, 2, s4
	s_and_saveexec_b64 s[4:5], vcc
	s_cbranch_execz .LBB0_1258
	ds_write_b128 v205, v[124:127]
	ds_write_b128 v205, v[60:63] offset:16
	ds_write_b128 v205, v[108:111] offset:512
	ds_write_b128 v205, v[44:47] offset:528
	ds_write_b128 v205, v[92:95] offset:2048
	ds_write_b128 v205, v[28:31] offset:2064
	ds_write_b128 v205, v[76:79] offset:2560
	ds_write_b128 v205, v[24:27] offset:2576
.LBB0_1258:
	s_or_b64 exec, exec, s[4:5]
	v_cmp_eq_u32_e64 s[10:11], 15, v201
	s_and_saveexec_b64 s[4:5], s[10:11]
	s_cbranch_execz .LBB0_1260
	ds_write_b128 v205, v[112:115] offset:1024
	ds_write_b128 v205, v[48:51] offset:1040
	ds_write_b128 v205, v[96:99] offset:1536
	ds_write_b128 v205, v[32:35] offset:1552
	ds_write_b128 v205, v[80:83] offset:3072
	ds_write_b128 v205, v[8:11] offset:3088
	ds_write_b128 v205, v[64:67] offset:3584
	ds_write_b128 v205, v[0:3] offset:3600
.LBB0_1260:
	s_or_b64 exec, exec, s[4:5]
	v_readlane_b32 s4, v254, 40
	s_nop 0
	v_lshlrev_b32_e32 v204, 2, v160
	v_or_b32_e32 v161, s4, v201
	v_add_u32_e32 v203, s87, v204
	v_readlane_b32 s4, v254, 42
	v_cmp_eq_u32_e64 s[8:9], 0, v161
	s_waitcnt lgkmcnt(0)
	s_barrier
	ds_read_b128 v[160:163], v203
	v_add_u32_e32 v202, s4, v204
	ds_read_b128 v[172:175], v202
	ds_read_b128 v[164:167], v203 offset:512
	ds_read_b128 v[168:171], v202 offset:512
	s_lshl_b32 s25, s14, 2
	s_mul_hi_i32 s4, s25, 0xb000
	s_waitcnt lgkmcnt(0)
	v_mov_b32_dpp v160, v112 row_shr:1 row_mask:0xf bank_mask:0xf
	v_mov_b32_dpp v161, v113 row_shr:1 row_mask:0xf bank_mask:0xf
	v_mov_b32_dpp v162, v114 row_shr:1 row_mask:0xf bank_mask:0xf
	v_mov_b32_dpp v163, v115 row_shr:1 row_mask:0xf bank_mask:0xf
	v_mov_b32_dpp v164, v96 row_shr:1 row_mask:0xf bank_mask:0xf
	v_mov_b32_dpp v165, v97 row_shr:1 row_mask:0xf bank_mask:0xf
	v_mov_b32_dpp v166, v98 row_shr:1 row_mask:0xf bank_mask:0xf
	v_mov_b32_dpp v167, v99 row_shr:1 row_mask:0xf bank_mask:0xf
	v_mov_b32_dpp v172, v124 row_shl:1 row_mask:0xf bank_mask:0xf
	v_mov_b32_dpp v173, v125 row_shl:1 row_mask:0xf bank_mask:0xf
	v_mov_b32_dpp v174, v126 row_shl:1 row_mask:0xf bank_mask:0xf
	v_mov_b32_dpp v175, v127 row_shl:1 row_mask:0xf bank_mask:0xf
	v_mov_b32_dpp v168, v108 row_shl:1 row_mask:0xf bank_mask:0xf
	v_mov_b32_dpp v169, v109 row_shl:1 row_mask:0xf bank_mask:0xf
	v_mov_b32_dpp v170, v110 row_shl:1 row_mask:0xf bank_mask:0xf
	v_mov_b32_dpp v171, v111 row_shl:1 row_mask:0xf bank_mask:0xf
	s_mul_i32 s5, s25, 0xb000
	s_waitcnt vmcnt(0)
	v_pk_fma_f32 v[206:207], v[124:125], v[148:149], v[128:129]
	v_pk_fma_f32 v[208:209], v[126:127], v[150:151], v[130:131]
	v_pk_fma_f32 v[160:161], v[132:133], v[160:161], v[206:207]
	v_pk_fma_f32 v[162:163], v[134:135], v[162:163], v[208:209]
	v_pk_fma_f32 v[206:207], v[108:109], v[144:145], v[136:137]
	v_pk_fma_f32 v[208:209], v[110:111], v[146:147], v[138:139]
	v_pk_fma_f32 v[164:165], v[140:141], v[164:165], v[206:207]
	v_pk_fma_f32 v[166:167], v[142:143], v[166:167], v[208:209]
	v_pk_fma_f32 v[160:161], v[120:121], v[152:153], v[160:161]
	v_pk_fma_f32 v[162:163], v[122:123], v[154:155], v[162:163]
	v_pk_fma_f32 v[164:165], v[104:105], v[156:157], v[164:165]
	v_pk_fma_f32 v[166:167], v[106:107], v[158:159], v[166:167]
	s_and_saveexec_b64 s[34:35], s[8:9]
	s_mov_b32 s75, 0x20000
	s_cbranch_execz .LBB0_1262
	s_add_u32 s36, s83, s5
	s_addc_u32 s37, s84, s4
	v_lshl_add_u64 v[206:207], v[176:177], 2, s[36:37]
	v_add_co_u32_e32 v208, vcc, 0x5000, v206
	global_store_dwordx4 v[206:207], v[160:163], off
	s_nop 0
	v_addc_co_u32_e32 v209, vcc, 0, v207, vcc
	global_store_dwordx4 v[208:209], v[164:167], off offset:2048
	v_add_co_u32_e32 v208, vcc, 0xb000, v206
	s_nop 1
	v_addc_co_u32_e32 v209, vcc, 0, v207, vcc
	v_add_co_u32_e32 v206, vcc, 0x10000, v206
	global_store_dwordx4 v[208:209], v[124:127], off
	s_nop 0
	v_addc_co_u32_e32 v207, vcc, 0, v207, vcc
	global_store_dwordx4 v[206:207], v[108:111], off offset:2048
